# phase 0: the 49 workgroups converting layer 0's W_in skip the (HBM-bound) x staging loop, which the other 207 workgroups cover
# baseline (speedup 1.0000x reference)
; __device__ __forceinline__ int tidx() { int t = threadIdx.x; asm volatile("" : "+v"(t)); return t; }
; __device__ void phase_init(KP& P_) {
;     ...
;     const size_t total = (size_t)MR * 256, GT = (size_t)gridDim.x * NTHR;
;     for (size_t i0 = (size_t)blockIdx.x * NTHR + tidx(); i0 < total; i0 += 4 * GT) {
;         f32x4 v[4];
; #pragma unroll
;         for (int q = 0; q < 4; ++q) { const size_t i = i0 + q * GT; v[q] = (f32x4){0.f, 0.f, 0.f, 0.f};
;             if (i < total) { const int row = (int)(i >> 8), c4 = (int)(i & 255) * 4; const int b = row / LP, r = row - b * LP;
.LBB0_929:
	v_readlane_b32 s6, v253, 7
	v_readlane_b32 s7, v253, 8
	s_load_dword s6, s[6:7], 0x0
	v_mov_b32_e32 v2, v198
	v_readlane_b32 s12, v253, 9
	v_readlane_b32 s13, v253, 10
	v_ashrrev_i32_e32 v3, 31, v2
	s_waitcnt vmcnt(0)
	s_sub_u32 s12, s12, 0x6200
	s_subb_u32 s13, s13, 0
	v_lshl_add_u64 v[18:19], s[12:13], 0, v[2:3]
	s_mov_b64 s[12:13], 0x410000
	v_cmp_gt_u64_e32 vcc, s[12:13], v[18:19]
	s_and_saveexec_b64 s[12:13], vcc
	s_cbranch_execz .LBB0_976
	s_load_dwordx4 s[48:51], s[30:31], 0x0
	v_readlane_b32 s14, v255, 23
	s_mov_b32 s7, s91
	s_waitcnt lgkmcnt(0)
	s_sub_i32 s6, s6, 49
	s_add_u32 s18, s86, 0x8200000
	v_readlane_b32 s15, v255, 24
	s_addc_u32 s19, s87, 0
	s_lshl_b64 s[20:21], s[6:7], 9
	s_lshl_b64 s[22:23], s[6:7], 10
	s_lshl_b64 s[24:25], s[6:7], 12
	s_sub_u32 s14, s14, 0x18800
	s_subb_u32 s15, s15, 0
	v_lshl_add_u64 v[2:3], v[2:3], 2, s[14:15]
	s_lshl_b64 s[34:35], s[6:7], 13
	s_mul_hi_u32 s37, s6, 0x600
	s_mul_i32 s36, s6, 0x600
	s_lshl_b64 s[46:47], s[6:7], 11
	s_mov_b64 s[52:53], 0
	s_branch .LBB0_932

; __device__ __forceinline__ int tidx() { int t = threadIdx.x; asm volatile("" : "+v"(t)); return t; }
; __device__ void phase_init(KP& P_) {
;     ...
;     const size_t total = (size_t)MR * 256, GT = (size_t)gridDim.x * NTHR;
;     for (size_t i0 = (size_t)blockIdx.x * NTHR + tidx(); i0 < total; i0 += 4 * GT) {
.Linit_fix:
	s_add_i32 s6, s6, 49
